# ffn_up epilogue: conv weight loads hoisted above the dump barrier
# speedup vs baseline: 1.0089x; 1.0051x over previous
.LBB0_1077:
	s_or_b64 exec, exec, s[4:5]
	v_lshl_or_b32 v132, s30, 7, v162
	v_ashrrev_i32_e32 v133, 31, v132
	s_sub_i32 s2, 0x4201, s31
	v_lshlrev_b64 v[128:129], 2, v[132:133]
	v_min_i32_e32 v170, s2, v164
	v_add_u32_e32 v180, s31, v165
	v_lshl_add_u64 v[136:137], s[16:17], 0, v[128:129]
	v_lshl_add_u64 v[134:135], s[0:1], 0, v[128:129]
	v_cmp_lt_i32_e64 s[2:3], v163, v170
	v_mul_hi_i32 v181, v180, s35
	v_lshl_add_u64 v[130:131], s[6:7], 0, v[128:129]
	v_lshl_add_u64 v[144:145], s[18:19], 0, v[128:129]
	v_lshl_add_u64 v[146:147], s[20:21], 0, v[128:129]
	v_lshl_add_u64 v[148:149], s[22:23], 0, v[128:129]
	global_load_dwordx2 v[138:139], v[136:137], off
	global_load_dwordx2 v[140:141], v[134:135], off
	global_load_dwordx2 v[142:143], v[130:131], off
	s_nop 0
	global_load_dwordx2 v[144:145], v[144:145], off
	s_nop 0
	global_load_dwordx2 v[146:147], v[146:147], off
	s_nop 0
	global_load_dwordx2 v[148:149], v[148:149], off
	v_lshl_add_u64 v[130:131], s[24:25], 0, v[128:129]
	v_lshl_add_u64 v[128:129], s[26:27], 0, v[128:129]
	global_load_dwordx2 v[150:151], v[130:131], off
	global_load_dwordx2 v[152:153], v[128:129], off
	s_waitcnt lgkmcnt(0)
	s_barrier
	s_and_saveexec_b64 s[30:31], s[2:3]
	s_cbranch_execz .LBB0_1080
	v_mov_b64_e32 v[128:129], s[14:15]
	v_mad_i64_i32 v[128:129], s[4:5], v180, s87, v[128:129]
	v_lshl_add_u64 v[154:155], v[132:133], 1, v[128:129]
	v_lshrrev_b32_e32 v128, 31, v181
	v_ashrrev_i32_e32 v129, 11, v181
	v_add_u32_e32 v128, v129, v128
	v_mul_i32_i24_e32 v128, 0x2100, v128
	v_sub_u32_e32 v182, v180, v128
	ds_read2_b64 v[128:131], v166 offset1:16
	ds_read_b64 v[160:161], v167
	ds_read_b64 v[158:159], v168
	s_mov_b64 s[40:41], 0
	v_mov_b32_e32 v183, v169
	v_mov_b32_e32 v184, v163
	s_waitcnt lgkmcnt(2)
	v_mov_b64_e32 v[156:157], v[128:129]
	s_waitcnt vmcnt(0)
	v_add_u32_e32 v236, 0xfffffeff, v182
	s_movk_i32 s40, 0x1fef
	v_cmp_le_u32_e64 s[4:5], s40, v236
	v_sub_u32_e32 v236, v170, v184
	v_cmp_gt_u32_e64 s[40:41], 15, v236
	s_or_b64 s[4:5], s[4:5], s[40:41]
	s_cmp_lg_u64 s[4:5], 0
	s_cbranch_scc0 .Lffnepi0_fast
	s_mov_b64 s[40:41], 0
	s_branch .LBB0_1079

.LBB0_1082:
	s_or_b64 exec, exec, s[4:5]
	v_or_b32_e32 v0, 64, v132
	v_ashrrev_i32_e32 v1, 31, v0
	v_lshlrev_b64 v[0:1], 2, v[0:1]
	v_lshl_add_u64 v[2:3], s[6:7], 0, v[0:1]
	v_lshl_add_u64 v[10:11], s[18:19], 0, v[0:1]
	v_lshl_add_u64 v[12:13], s[20:21], 0, v[0:1]
	v_lshl_add_u64 v[14:15], s[22:23], 0, v[0:1]
	global_load_dwordx2 v[4:5], v[136:137], off offset:256
	global_load_dwordx2 v[6:7], v[134:135], off offset:256
	global_load_dwordx2 v[8:9], v[2:3], off
	s_nop 0
	global_load_dwordx2 v[10:11], v[10:11], off
	s_nop 0
	global_load_dwordx2 v[12:13], v[12:13], off
	s_nop 0
	global_load_dwordx2 v[14:15], v[14:15], off
	v_lshl_add_u64 v[2:3], s[24:25], 0, v[0:1]
	v_lshl_add_u64 v[0:1], s[26:27], 0, v[0:1]
	global_load_dwordx2 v[16:17], v[2:3], off
	global_load_dwordx2 v[18:19], v[0:1], off
	s_waitcnt lgkmcnt(0)
	s_barrier
	s_and_saveexec_b64 s[4:5], s[2:3]
	s_cbranch_execz .LBB0_1066
	v_mov_b64_e32 v[0:1], s[14:15]
	v_mad_i64_i32 v[0:1], s[2:3], v180, s87, v[0:1]
	v_lshl_add_u64 v[0:1], v[132:133], 1, v[0:1]
	v_lshl_add_u64 v[20:21], v[0:1], 0, s[66:67]
	v_lshrrev_b32_e32 v0, 31, v181
	v_ashrrev_i32_e32 v1, 11, v181
	v_add_u32_e32 v0, v1, v0
	v_mul_i32_i24_e32 v0, 0x2100, v0
	v_sub_u32_e32 v28, v180, v0
	ds_read2_b64 v[0:3], v166 offset1:16
	ds_read_b64 v[26:27], v167
	ds_read_b64 v[24:25], v168
	s_mov_b64 s[2:3], 0
	v_mov_b32_e32 v29, v169
	v_mov_b32_e32 v30, v163
	s_waitcnt lgkmcnt(2)
	v_mov_b64_e32 v[22:23], v[0:1]
	s_waitcnt vmcnt(0)
	v_add_u32_e32 v118, 0xfffffeff, v28
	v_cmp_le_u32_e32 vcc, 0x1fef, v118
	v_sub_u32_e32 v118, v170, v30
	v_cmp_gt_u32_e64 s[2:3], 15, v118
	s_or_b64 vcc, vcc, s[2:3]
	s_cmp_lg_u64 vcc, 0
	s_cbranch_scc0 .Lffnepi1_fast
	s_mov_b64 s[2:3], 0
	s_branch .LBB0_1084
